# stack with scan B waits that do not rely on load/store completion order
# baseline (speedup 1.0000x reference)
.LBB0_1021:
	v_lshl_add_u64 v[140:141], v[134:135], 0, v[188:189]
	v_add_co_u32_e32 v142, vcc, 0x23a00000, v140
	s_mov_b32 s1, 0x1ba01000
	s_nop 0
	v_addc_co_u32_e32 v143, vcc, 0, v141, vcc
	v_add_co_u32_e32 v142, vcc, 0x23a01000, v140
	s_mov_b64 s[6:7], 0x8000
	s_nop 0
	v_addc_co_u32_e32 v143, vcc, 0, v141, vcc
	v_lshl_add_u64 v[142:143], v[132:133], 0, v[188:189]
	s_mov_b32 s99, 0
	s_mov_b32 s98, 0x23a00800
	v_lshl_add_u64 v[144:145], v[140:141], 0, s[98:99]
	global_load_dwordx2 v[162:163], v[144:145], off offset:-2048
	global_load_dwordx2 v[164:165], v[144:145], off offset:2048
	s_mov_b32 s98, 0x1fa00800
	v_lshl_add_u64 v[148:149], v[142:143], 0, s[98:99]
	global_load_dwordx2 v[166:167], v[148:149], off offset:-2048
	s_mov_b32 s98, 0x1ba01000
	v_lshl_add_u64 v[146:147], v[140:141], 0, s[98:99]
	global_load_dwordx2 v[168:169], v[146:147], off
	s_mov_b32 s98, 0x23a02800
	v_lshl_add_u64 v[144:145], v[140:141], 0, s[98:99]
	global_load_dwordx2 v[170:171], v[144:145], off offset:-2048
	global_load_dwordx2 v[172:173], v[144:145], off offset:2048
	global_load_dwordx2 v[174:175], v[148:149], off offset:2048
	s_mov_b32 s98, 0x1ba03000
	v_lshl_add_u64 v[146:147], v[140:141], 0, s[98:99]
	global_load_dwordx2 v[176:177], v[146:147], off
	s_mov_b32 s98, 0x23a04800
	v_lshl_add_u64 v[144:145], v[140:141], 0, s[98:99]
	global_load_dwordx2 v[178:179], v[144:145], off offset:-2048
	global_load_dwordx2 v[182:183], v[144:145], off offset:2048
	s_mov_b32 s98, 0x1fa02800
	v_lshl_add_u64 v[148:149], v[142:143], 0, s[98:99]
	global_load_dwordx2 v[184:185], v[148:149], off offset:-2048
	s_mov_b32 s98, 0x1ba05000
	v_lshl_add_u64 v[146:147], v[140:141], 0, s[98:99]
	global_load_dwordx2 v[186:187], v[146:147], off
	s_mov_b32 s98, 0x23a06800
	v_lshl_add_u64 v[144:145], v[140:141], 0, s[98:99]
	global_load_dwordx2 v[190:191], v[144:145], off offset:-2048
	global_load_dwordx2 v[194:195], v[144:145], off offset:2048
	global_load_dwordx2 v[196:197], v[148:149], off offset:2048
	s_mov_b32 s98, 0x1ba07000
	v_lshl_add_u64 v[146:147], v[140:141], 0, s[98:99]
	global_load_dwordx2 v[198:199], v[146:147], off
	s_mov_b32 s98, 0x23a08800
	v_lshl_add_u64 v[144:145], v[140:141], 0, s[98:99]
	global_load_dwordx2 v[200:201], v[144:145], off offset:-2048
	global_load_dwordx2 v[202:203], v[144:145], off offset:2048
	s_mov_b32 s98, 0x1fa04800
	v_lshl_add_u64 v[148:149], v[142:143], 0, s[98:99]
	global_load_dwordx2 v[204:205], v[148:149], off offset:-2048
	s_mov_b32 s98, 0x1ba09000
	v_lshl_add_u64 v[146:147], v[140:141], 0, s[98:99]
	global_load_dwordx2 v[206:207], v[146:147], off
	s_mov_b32 s98, 0x23a0a800
	v_lshl_add_u64 v[144:145], v[140:141], 0, s[98:99]
	global_load_dwordx2 v[208:209], v[144:145], off offset:-2048
	global_load_dwordx2 v[210:211], v[144:145], off offset:2048
	global_load_dwordx2 v[212:213], v[148:149], off offset:2048
	s_mov_b32 s98, 0x1ba0b000
	v_lshl_add_u64 v[146:147], v[140:141], 0, s[98:99]
	global_load_dwordx2 v[214:215], v[146:147], off
	s_mov_b32 s98, 0x23a0c800
	v_lshl_add_u64 v[144:145], v[140:141], 0, s[98:99]
	global_load_dwordx2 v[216:217], v[144:145], off offset:-2048
	global_load_dwordx2 v[218:219], v[144:145], off offset:2048
	s_mov_b32 s98, 0x1fa06800
	v_lshl_add_u64 v[148:149], v[142:143], 0, s[98:99]
	global_load_dwordx2 v[222:223], v[148:149], off offset:-2048
	s_mov_b32 s98, 0x1ba0d000
	v_lshl_add_u64 v[146:147], v[140:141], 0, s[98:99]
	global_load_dwordx2 v[224:225], v[146:147], off
	s_mov_b32 s98, 0x23a0e800
	v_lshl_add_u64 v[144:145], v[140:141], 0, s[98:99]
	global_load_dwordx2 v[226:227], v[144:145], off offset:-2048
	global_load_dwordx2 v[232:233], v[144:145], off offset:2048
	global_load_dwordx2 v[234:235], v[148:149], off offset:2048
	s_mov_b32 s98, 0x1ba0f000
	v_lshl_add_u64 v[146:147], v[140:141], 0, s[98:99]
	global_load_dwordx2 v[238:239], v[146:147], off
	v_add_co_u32_e32 v148, vcc, 0x1fa00000, v142
	v_lshl_add_u64 v[132:133], v[132:133], 0, s[6:7]
	s_nop 0
	v_addc_co_u32_e32 v149, vcc, 0, v143, vcc
	s_mov_b64 s[6:7], 0x10000
	s_add_i32 s0, s0, -8
	v_lshl_add_u64 v[134:135], v[134:135], 0, s[6:7]
	s_cmp_eq_u32 s0, 0
	s_waitcnt vmcnt(28)
	v_lshlrev_b32_e32 v150, 16, v162
	v_and_b32_e32 v151, 0xffff0000, v162
	v_lshlrev_b32_e32 v154, 16, v163
	v_and_b32_e32 v155, 0xffff0000, v163
	v_lshlrev_b32_e32 v144, 16, v164
	v_and_b32_e32 v145, 0xffff0000, v164
	v_add_f32_e32 v146, v68, v150
	v_mul_f32_e32 v146, 0xbfb8aa3b, v146
	v_exp_f32_e32 v146, v146
	v_lshlrev_b32_e32 v156, 16, v165
	v_and_b32_e32 v157, 0xffff0000, v165
	v_add_f32_e32 v144, v64, v144
	v_add_f32_e32 v146, 1.0, v146
	v_rcp_f32_e32 v146, v146
	v_add_f32_e32 v145, v65, v145
	v_mul_f32_e32 v144, 0xbfb8aa3b, v144
	v_mul_f32_e32 v145, 0xbfb8aa3b, v145
	v_mul_f32_e32 v146, v72, v146
	v_exp_f32_e32 v146, v146
	v_exp_f32_e32 v144, v144
	v_exp_f32_e32 v145, v145
	v_and_b32_e32 v153, 0xffff0000, v166
	v_sub_f32_e32 v147, 1.0, v146
	v_add_f32_e32 v150, 1.0, v146
	v_mul_f32_e32 v147, v147, v150
	v_sqrt_f32_e32 v150, v147
	v_add_f32_e32 v147, v69, v151
	v_mul_f32_e32 v147, 0xbfb8aa3b, v147
	v_exp_f32_e32 v147, v147
	v_add_f32_e32 v144, 1.0, v144
	v_add_f32_e32 v145, 1.0, v145
	v_rcp_f32_e32 v144, v144
	v_add_f32_e32 v147, 1.0, v147
	v_rcp_f32_e32 v147, v147
	v_rcp_f32_e32 v145, v145
	v_mul_f32_e32 v147, v73, v147
	v_exp_f32_e32 v147, v147
	s_nop 0
	v_sub_f32_e32 v151, 1.0, v147
	v_add_f32_e32 v152, 1.0, v147
	v_mul_f32_e32 v151, v151, v152
	v_sqrt_f32_e32 v151, v151
	v_lshlrev_b32_e32 v152, 16, v166
	v_pk_mul_f32 v[144:145], v[144:145], v[152:153]
	v_add_f32_e32 v148, v70, v154
	v_pk_mul_f32 v[144:145], v[144:145], v[150:151]
	v_mul_f32_e32 v148, 0xbfb8aa3b, v148
	v_pk_fma_f32 v[138:139], v[138:139], v[146:147], v[144:145]
	v_add_co_u32_e32 v144, vcc, s1, v140
	v_exp_f32_e32 v148, v148
	s_nop 0
	v_addc_co_u32_e32 v145, vcc, 0, v141, vcc
	v_add_f32_e32 v148, 1.0, v148
	v_rcp_f32_e32 v148, v148
	v_add_f32_e32 v150, v66, v156
	v_mul_f32_e32 v150, 0xbfb8aa3b, v150
	v_exp_f32_e32 v150, v150
	v_mul_f32_e32 v148, v74, v148
	v_exp_f32_e32 v152, v148
	s_mov_b32 s1, 0x21a01000
	v_add_f32_e32 v150, 1.0, v150
	v_rcp_f32_e32 v150, v150
	v_sub_f32_e32 v148, 1.0, v152
	v_add_f32_e32 v151, 1.0, v152
	v_mul_f32_e32 v148, v148, v151
	v_sqrt_f32_e32 v154, v148
	v_add_f32_e32 v148, v71, v155
	v_mul_f32_e32 v148, 0xbfb8aa3b, v148
	v_exp_f32_e32 v148, v148
	v_add_f32_e32 v151, v67, v157
	v_mul_f32_e32 v151, 0xbfb8aa3b, v151
	v_exp_f32_e32 v151, v151
	v_add_f32_e32 v148, 1.0, v148
	v_rcp_f32_e32 v148, v148
	v_add_f32_e32 v151, 1.0, v151
	v_rcp_f32_e32 v151, v151
	v_mul_f32_e32 v148, v75, v148
	v_exp_f32_e32 v153, v148
	v_lshlrev_b32_e32 v146, 16, v168
	v_sub_f32_e32 v148, 1.0, v153
	v_add_f32_e32 v155, 1.0, v153
	v_mul_f32_e32 v148, v148, v155
	v_sqrt_f32_e32 v155, v148
	v_lshlrev_b32_e32 v148, 16, v167
	v_and_b32_e32 v149, 0xffff0000, v167
	v_pk_mul_f32 v[148:149], v[150:151], v[148:149]
	v_and_b32_e32 v147, 0xffff0000, v168
	v_pk_mul_f32 v[148:149], v[148:149], v[154:155]
	v_pk_mul_f32 v[146:147], v[138:139], v[146:147]
	v_pk_fma_f32 v[136:137], v[136:137], v[152:153], v[148:149]
	v_cvt_pk_bf16_f32 v144, v146, v147
	v_lshlrev_b32_e32 v146, 16, v169
	v_and_b32_e32 v147, 0xffff0000, v169
	v_pk_mul_f32 v[146:147], v[136:137], v[146:147]
	s_nop 0
	v_cvt_pk_bf16_f32 v145, v146, v147
	v_add_co_u32_e32 v146, vcc, s1, v142
	s_mov_b32 s1, 0x23a03000
	s_nop 0
	v_addc_co_u32_e32 v147, vcc, 0, v143, vcc
	global_store_dwordx2 v[146:147], v[144:145], off offset:-4096
	v_add_co_u32_e32 v144, vcc, s1, v140
	s_mov_b32 s1, 0x1fa02000
	s_nop 0
	v_addc_co_u32_e32 v145, vcc, 0, v141, vcc
	s_nop 0
	v_add_co_u32_e32 v150, vcc, s1, v142
	s_mov_b32 s1, 0x1ba03000
	s_nop 0
	v_addc_co_u32_e32 v151, vcc, 0, v143, vcc
	s_waitcnt vmcnt(24)
	v_lshlrev_b32_e32 v154, 16, v170
	v_and_b32_e32 v155, 0xffff0000, v170
	v_lshlrev_b32_e32 v158, 16, v171
	v_and_b32_e32 v159, 0xffff0000, v171
	v_lshlrev_b32_e32 v148, 16, v172
	v_and_b32_e32 v149, 0xffff0000, v172
	v_add_f32_e32 v144, v68, v154
	v_mul_f32_e32 v144, 0xbfb8aa3b, v144
	v_exp_f32_e32 v144, v144
	v_lshlrev_b32_e32 v160, 16, v173
	v_and_b32_e32 v161, 0xffff0000, v173
	v_and_b32_e32 v157, 0xffff0000, v174
	v_add_f32_e32 v144, 1.0, v144
	v_rcp_f32_e32 v145, v144
	v_add_f32_e32 v144, v64, v148
	v_mul_f32_e32 v144, 0xbfb8aa3b, v144
	v_exp_f32_e32 v144, v144
	v_mul_f32_e32 v145, v72, v145
	v_exp_f32_e32 v148, v145
	v_add_f32_e32 v144, 1.0, v144
	v_rcp_f32_e32 v144, v144
	v_sub_f32_e32 v145, 1.0, v148
	v_add_f32_e32 v154, 1.0, v148
	v_mul_f32_e32 v145, v145, v154
	v_sqrt_f32_e32 v154, v145
	v_add_f32_e32 v145, v69, v155
	v_mul_f32_e32 v145, 0xbfb8aa3b, v145
	v_exp_f32_e32 v145, v145
	s_nop 0
	v_add_f32_e32 v145, 1.0, v145
	v_rcp_f32_e32 v155, v145
	v_add_f32_e32 v145, v65, v149
	v_mul_f32_e32 v145, 0xbfb8aa3b, v145
	v_exp_f32_e32 v145, v145
	v_mul_f32_e32 v149, v73, v155
	v_exp_f32_e32 v149, v149
	v_add_f32_e32 v145, 1.0, v145
	v_rcp_f32_e32 v145, v145
	v_sub_f32_e32 v155, 1.0, v149
	v_add_f32_e32 v156, 1.0, v149
	v_mul_f32_e32 v155, v155, v156
	v_sqrt_f32_e32 v155, v155
	v_lshlrev_b32_e32 v156, 16, v174
	v_pk_mul_f32 v[144:145], v[144:145], v[156:157]
	v_add_f32_e32 v152, v70, v158
	v_pk_mul_f32 v[144:145], v[144:145], v[154:155]
	v_mul_f32_e32 v152, 0xbfb8aa3b, v152
	v_pk_fma_f32 v[138:139], v[138:139], v[148:149], v[144:145]
	v_add_co_u32_e32 v144, vcc, s1, v140
	v_exp_f32_e32 v152, v152
	s_nop 0
	v_addc_co_u32_e32 v145, vcc, 0, v141, vcc
	v_add_f32_e32 v152, 1.0, v152
	v_rcp_f32_e32 v152, v152
	v_add_f32_e32 v154, v66, v160
	v_mul_f32_e32 v154, 0xbfb8aa3b, v154
	v_exp_f32_e32 v154, v154
	v_mul_f32_e32 v152, v74, v152
	v_exp_f32_e32 v156, v152
	s_mov_b32 s1, 0x23a05000
	v_add_f32_e32 v154, 1.0, v154
	v_rcp_f32_e32 v154, v154
	v_sub_f32_e32 v152, 1.0, v156
	v_add_f32_e32 v155, 1.0, v156
	v_mul_f32_e32 v152, v152, v155
	v_sqrt_f32_e32 v158, v152
	v_add_f32_e32 v152, v71, v159
	v_mul_f32_e32 v152, 0xbfb8aa3b, v152
	v_exp_f32_e32 v152, v152
	v_add_f32_e32 v155, v67, v161
	v_mul_f32_e32 v155, 0xbfb8aa3b, v155
	v_exp_f32_e32 v155, v155
	v_add_f32_e32 v152, 1.0, v152
	v_rcp_f32_e32 v152, v152
	v_add_f32_e32 v155, 1.0, v155
	v_rcp_f32_e32 v155, v155
	v_mul_f32_e32 v152, v75, v152
	v_exp_f32_e32 v157, v152
	v_lshlrev_b32_e32 v148, 16, v176
	v_sub_f32_e32 v152, 1.0, v157
	v_add_f32_e32 v159, 1.0, v157
	v_mul_f32_e32 v152, v152, v159
	v_sqrt_f32_e32 v159, v152
	v_lshlrev_b32_e32 v152, 16, v175
	v_and_b32_e32 v153, 0xffff0000, v175
	v_pk_mul_f32 v[152:153], v[154:155], v[152:153]
	v_and_b32_e32 v149, 0xffff0000, v176
	v_pk_mul_f32 v[152:153], v[152:153], v[158:159]
	v_pk_mul_f32 v[148:149], v[138:139], v[148:149]
	v_pk_fma_f32 v[136:137], v[136:137], v[156:157], v[152:153]
	v_cvt_pk_bf16_f32 v144, v148, v149
	v_lshlrev_b32_e32 v148, 16, v177
	v_and_b32_e32 v149, 0xffff0000, v177
	v_pk_mul_f32 v[148:149], v[136:137], v[148:149]
	s_nop 0
	v_cvt_pk_bf16_f32 v145, v148, v149
	global_store_dwordx2 v[146:147], v[144:145], off
	v_add_co_u32_e32 v144, vcc, s1, v140
	s_mov_b32 s1, 0x1ba05000
	s_nop 0
	v_addc_co_u32_e32 v145, vcc, 0, v141, vcc
	s_nop 0
	s_nop 0
	s_waitcnt vmcnt(20)
	v_lshlrev_b32_e32 v150, 16, v178
	v_and_b32_e32 v151, 0xffff0000, v178
	v_lshlrev_b32_e32 v154, 16, v179
	v_and_b32_e32 v155, 0xffff0000, v179
	v_lshlrev_b32_e32 v146, 16, v182
	v_and_b32_e32 v147, 0xffff0000, v182
	v_add_f32_e32 v144, v68, v150
	v_mul_f32_e32 v144, 0xbfb8aa3b, v144
	v_exp_f32_e32 v144, v144
	v_lshlrev_b32_e32 v156, 16, v183
	v_and_b32_e32 v157, 0xffff0000, v183
	v_and_b32_e32 v153, 0xffff0000, v184
	v_add_f32_e32 v144, 1.0, v144
	v_rcp_f32_e32 v145, v144
	v_add_f32_e32 v144, v64, v146
	v_mul_f32_e32 v144, 0xbfb8aa3b, v144
	v_exp_f32_e32 v144, v144
	v_mul_f32_e32 v145, v72, v145
	v_exp_f32_e32 v146, v145
	v_add_f32_e32 v144, 1.0, v144
	v_rcp_f32_e32 v144, v144
	v_sub_f32_e32 v145, 1.0, v146
	v_add_f32_e32 v150, 1.0, v146
	v_mul_f32_e32 v145, v145, v150
	v_sqrt_f32_e32 v150, v145
	v_add_f32_e32 v145, v69, v151
	v_mul_f32_e32 v145, 0xbfb8aa3b, v145
	v_exp_f32_e32 v145, v145
	s_nop 0
	v_add_f32_e32 v145, 1.0, v145
	v_rcp_f32_e32 v151, v145
	v_add_f32_e32 v145, v65, v147
	v_mul_f32_e32 v145, 0xbfb8aa3b, v145
	v_exp_f32_e32 v145, v145
	v_mul_f32_e32 v147, v73, v151
	v_exp_f32_e32 v147, v147
	v_add_f32_e32 v145, 1.0, v145
	v_rcp_f32_e32 v145, v145
	v_sub_f32_e32 v151, 1.0, v147
	v_add_f32_e32 v152, 1.0, v147
	v_mul_f32_e32 v151, v151, v152
	v_sqrt_f32_e32 v151, v151
	v_lshlrev_b32_e32 v152, 16, v184
	v_pk_mul_f32 v[144:145], v[144:145], v[152:153]
	v_add_f32_e32 v148, v70, v154
	v_pk_mul_f32 v[144:145], v[144:145], v[150:151]
	v_mul_f32_e32 v148, 0xbfb8aa3b, v148
	v_pk_fma_f32 v[138:139], v[138:139], v[146:147], v[144:145]
	v_add_co_u32_e32 v144, vcc, s1, v140
	v_exp_f32_e32 v148, v148
	s_nop 0
	v_addc_co_u32_e32 v145, vcc, 0, v141, vcc
	v_add_f32_e32 v148, 1.0, v148
	v_rcp_f32_e32 v148, v148
	v_add_f32_e32 v150, v66, v156
	v_mul_f32_e32 v150, 0xbfb8aa3b, v150
	v_exp_f32_e32 v150, v150
	v_mul_f32_e32 v148, v74, v148
	v_exp_f32_e32 v152, v148
	s_mov_b32 s1, 0x21a03000
	v_add_f32_e32 v150, 1.0, v150
	v_rcp_f32_e32 v150, v150
	v_sub_f32_e32 v148, 1.0, v152
	v_add_f32_e32 v151, 1.0, v152
	v_mul_f32_e32 v148, v148, v151
	v_sqrt_f32_e32 v154, v148
	v_add_f32_e32 v148, v71, v155
	v_mul_f32_e32 v148, 0xbfb8aa3b, v148
	v_exp_f32_e32 v148, v148
	v_add_f32_e32 v151, v67, v157
	v_mul_f32_e32 v151, 0xbfb8aa3b, v151
	v_exp_f32_e32 v151, v151
	v_add_f32_e32 v148, 1.0, v148
	v_rcp_f32_e32 v148, v148
	v_add_f32_e32 v151, 1.0, v151
	v_rcp_f32_e32 v151, v151
	v_mul_f32_e32 v148, v75, v148
	v_exp_f32_e32 v153, v148
	v_lshlrev_b32_e32 v146, 16, v186
	v_sub_f32_e32 v148, 1.0, v153
	v_add_f32_e32 v155, 1.0, v153
	v_mul_f32_e32 v148, v148, v155
	v_sqrt_f32_e32 v155, v148
	v_lshlrev_b32_e32 v148, 16, v185
	v_and_b32_e32 v149, 0xffff0000, v185
	v_pk_mul_f32 v[148:149], v[150:151], v[148:149]
	v_and_b32_e32 v147, 0xffff0000, v186
	v_pk_mul_f32 v[148:149], v[148:149], v[154:155]
	v_pk_mul_f32 v[146:147], v[138:139], v[146:147]
	v_pk_fma_f32 v[136:137], v[136:137], v[152:153], v[148:149]
	v_cvt_pk_bf16_f32 v144, v146, v147
	v_lshlrev_b32_e32 v146, 16, v187
	v_and_b32_e32 v147, 0xffff0000, v187
	v_pk_mul_f32 v[146:147], v[136:137], v[146:147]
	s_nop 0
	v_cvt_pk_bf16_f32 v145, v146, v147
	v_add_co_u32_e32 v146, vcc, s1, v142
	s_mov_b32 s1, 0x23a07000
	s_nop 0
	v_addc_co_u32_e32 v147, vcc, 0, v143, vcc
	global_store_dwordx2 v[146:147], v[144:145], off offset:-4096
	v_add_co_u32_e32 v144, vcc, s1, v140
	s_mov_b32 s1, 0x1fa04000
	s_nop 0
	v_addc_co_u32_e32 v145, vcc, 0, v141, vcc
	s_nop 0
	v_add_co_u32_e32 v150, vcc, s1, v142
	s_mov_b32 s1, 0x1ba07000
	s_nop 0
	v_addc_co_u32_e32 v151, vcc, 0, v143, vcc
	s_waitcnt vmcnt(16)
	v_lshlrev_b32_e32 v154, 16, v190
	v_and_b32_e32 v155, 0xffff0000, v190
	v_lshlrev_b32_e32 v158, 16, v191
	v_and_b32_e32 v159, 0xffff0000, v191
	v_lshlrev_b32_e32 v148, 16, v194
	v_and_b32_e32 v149, 0xffff0000, v194
	v_add_f32_e32 v144, v68, v154
	v_mul_f32_e32 v144, 0xbfb8aa3b, v144
	v_exp_f32_e32 v144, v144
	v_lshlrev_b32_e32 v160, 16, v195
	v_and_b32_e32 v161, 0xffff0000, v195
	v_and_b32_e32 v157, 0xffff0000, v196
	v_add_f32_e32 v144, 1.0, v144
	v_rcp_f32_e32 v145, v144
	v_add_f32_e32 v144, v64, v148
	v_mul_f32_e32 v144, 0xbfb8aa3b, v144
	v_exp_f32_e32 v144, v144
	v_mul_f32_e32 v145, v72, v145
	v_exp_f32_e32 v148, v145
	v_add_f32_e32 v144, 1.0, v144
	v_rcp_f32_e32 v144, v144
	v_sub_f32_e32 v145, 1.0, v148
	v_add_f32_e32 v154, 1.0, v148
	v_mul_f32_e32 v145, v145, v154
	v_sqrt_f32_e32 v154, v145
	v_add_f32_e32 v145, v69, v155
	v_mul_f32_e32 v145, 0xbfb8aa3b, v145
	v_exp_f32_e32 v145, v145
	s_nop 0
	v_add_f32_e32 v145, 1.0, v145
	v_rcp_f32_e32 v155, v145
	v_add_f32_e32 v145, v65, v149
	v_mul_f32_e32 v145, 0xbfb8aa3b, v145
	v_exp_f32_e32 v145, v145
	v_mul_f32_e32 v149, v73, v155
	v_exp_f32_e32 v149, v149
	v_add_f32_e32 v145, 1.0, v145
	v_rcp_f32_e32 v145, v145
	v_sub_f32_e32 v155, 1.0, v149
	v_add_f32_e32 v156, 1.0, v149
	v_mul_f32_e32 v155, v155, v156
	v_sqrt_f32_e32 v155, v155
	v_lshlrev_b32_e32 v156, 16, v196
	v_pk_mul_f32 v[144:145], v[144:145], v[156:157]
	v_add_f32_e32 v152, v70, v158
	v_pk_mul_f32 v[144:145], v[144:145], v[154:155]
	v_mul_f32_e32 v152, 0xbfb8aa3b, v152
	v_pk_fma_f32 v[138:139], v[138:139], v[148:149], v[144:145]
	v_add_co_u32_e32 v144, vcc, s1, v140
	v_exp_f32_e32 v152, v152
	s_nop 0
	v_addc_co_u32_e32 v145, vcc, 0, v141, vcc
	v_add_f32_e32 v152, 1.0, v152
	v_rcp_f32_e32 v152, v152
	v_add_f32_e32 v154, v66, v160
	v_mul_f32_e32 v154, 0xbfb8aa3b, v154
	v_exp_f32_e32 v154, v154
	v_mul_f32_e32 v152, v74, v152
	v_exp_f32_e32 v156, v152
	s_mov_b32 s1, 0x23a09000
	v_add_f32_e32 v154, 1.0, v154
	v_rcp_f32_e32 v154, v154
	v_sub_f32_e32 v152, 1.0, v156
	v_add_f32_e32 v155, 1.0, v156
	v_mul_f32_e32 v152, v152, v155
	v_sqrt_f32_e32 v158, v152
	v_add_f32_e32 v152, v71, v159
	v_mul_f32_e32 v152, 0xbfb8aa3b, v152
	v_exp_f32_e32 v152, v152
	v_add_f32_e32 v155, v67, v161
	v_mul_f32_e32 v155, 0xbfb8aa3b, v155
	v_exp_f32_e32 v155, v155
	v_add_f32_e32 v152, 1.0, v152
	v_rcp_f32_e32 v152, v152
	v_add_f32_e32 v155, 1.0, v155
	v_rcp_f32_e32 v155, v155
	v_mul_f32_e32 v152, v75, v152
	v_exp_f32_e32 v157, v152
	v_lshlrev_b32_e32 v148, 16, v198
	v_sub_f32_e32 v152, 1.0, v157
	v_add_f32_e32 v159, 1.0, v157
	v_mul_f32_e32 v152, v152, v159
	v_sqrt_f32_e32 v159, v152
	v_lshlrev_b32_e32 v152, 16, v197
	v_and_b32_e32 v153, 0xffff0000, v197
	v_pk_mul_f32 v[152:153], v[154:155], v[152:153]
	v_and_b32_e32 v149, 0xffff0000, v198
	v_pk_mul_f32 v[152:153], v[152:153], v[158:159]
	v_pk_mul_f32 v[148:149], v[138:139], v[148:149]
	v_pk_fma_f32 v[136:137], v[136:137], v[156:157], v[152:153]
	v_cvt_pk_bf16_f32 v144, v148, v149
	v_lshlrev_b32_e32 v148, 16, v199
	v_and_b32_e32 v149, 0xffff0000, v199
	v_pk_mul_f32 v[148:149], v[136:137], v[148:149]
	s_nop 0
	v_cvt_pk_bf16_f32 v145, v148, v149
	global_store_dwordx2 v[146:147], v[144:145], off
	v_add_co_u32_e32 v144, vcc, s1, v140
	s_mov_b32 s1, 0x1ba09000
	s_nop 0
	v_addc_co_u32_e32 v145, vcc, 0, v141, vcc
	s_nop 0
	s_nop 0
	s_waitcnt vmcnt(12)
	v_lshlrev_b32_e32 v150, 16, v200
	v_and_b32_e32 v151, 0xffff0000, v200
	v_lshlrev_b32_e32 v154, 16, v201
	v_and_b32_e32 v155, 0xffff0000, v201
	v_lshlrev_b32_e32 v146, 16, v202
	v_and_b32_e32 v147, 0xffff0000, v202
	v_add_f32_e32 v144, v68, v150
	v_mul_f32_e32 v144, 0xbfb8aa3b, v144
	v_exp_f32_e32 v144, v144
	v_lshlrev_b32_e32 v156, 16, v203
	v_and_b32_e32 v157, 0xffff0000, v203
	v_and_b32_e32 v153, 0xffff0000, v204
	v_add_f32_e32 v144, 1.0, v144
	v_rcp_f32_e32 v145, v144
	v_add_f32_e32 v144, v64, v146
	v_mul_f32_e32 v144, 0xbfb8aa3b, v144
	v_exp_f32_e32 v144, v144
	v_mul_f32_e32 v145, v72, v145
	v_exp_f32_e32 v146, v145
	v_add_f32_e32 v144, 1.0, v144
	v_rcp_f32_e32 v144, v144
	v_sub_f32_e32 v145, 1.0, v146
	v_add_f32_e32 v150, 1.0, v146
	v_mul_f32_e32 v145, v145, v150
	v_sqrt_f32_e32 v150, v145
	v_add_f32_e32 v145, v69, v151
	v_mul_f32_e32 v145, 0xbfb8aa3b, v145
	v_exp_f32_e32 v145, v145
	s_nop 0
	v_add_f32_e32 v145, 1.0, v145
	v_rcp_f32_e32 v151, v145
	v_add_f32_e32 v145, v65, v147
	v_mul_f32_e32 v145, 0xbfb8aa3b, v145
	v_exp_f32_e32 v145, v145
	v_mul_f32_e32 v147, v73, v151
	v_exp_f32_e32 v147, v147
	v_add_f32_e32 v145, 1.0, v145
	v_rcp_f32_e32 v145, v145
	v_sub_f32_e32 v151, 1.0, v147
	v_add_f32_e32 v152, 1.0, v147
	v_mul_f32_e32 v151, v151, v152
	v_sqrt_f32_e32 v151, v151
	v_lshlrev_b32_e32 v152, 16, v204
	v_pk_mul_f32 v[144:145], v[144:145], v[152:153]
	v_add_f32_e32 v148, v70, v154
	v_pk_mul_f32 v[144:145], v[144:145], v[150:151]
	v_mul_f32_e32 v148, 0xbfb8aa3b, v148
	v_pk_fma_f32 v[138:139], v[138:139], v[146:147], v[144:145]
	v_add_co_u32_e32 v144, vcc, s1, v140
	v_exp_f32_e32 v148, v148
	s_nop 0
	v_addc_co_u32_e32 v145, vcc, 0, v141, vcc
	v_add_f32_e32 v148, 1.0, v148
	v_rcp_f32_e32 v148, v148
	v_add_f32_e32 v150, v66, v156
	v_mul_f32_e32 v150, 0xbfb8aa3b, v150
	v_exp_f32_e32 v150, v150
	v_mul_f32_e32 v148, v74, v148
	v_exp_f32_e32 v152, v148
	s_mov_b32 s1, 0x21a05000
	v_add_f32_e32 v150, 1.0, v150
	v_rcp_f32_e32 v150, v150
	v_sub_f32_e32 v148, 1.0, v152
	v_add_f32_e32 v151, 1.0, v152
	v_mul_f32_e32 v148, v148, v151
	v_sqrt_f32_e32 v154, v148
	v_add_f32_e32 v148, v71, v155
	v_mul_f32_e32 v148, 0xbfb8aa3b, v148
	v_exp_f32_e32 v148, v148
	v_add_f32_e32 v151, v67, v157
	v_mul_f32_e32 v151, 0xbfb8aa3b, v151
	v_exp_f32_e32 v151, v151
	v_add_f32_e32 v148, 1.0, v148
	v_rcp_f32_e32 v148, v148
	v_add_f32_e32 v151, 1.0, v151
	v_rcp_f32_e32 v151, v151
	v_mul_f32_e32 v148, v75, v148
	v_exp_f32_e32 v153, v148
	v_lshlrev_b32_e32 v146, 16, v206
	v_sub_f32_e32 v148, 1.0, v153
	v_add_f32_e32 v155, 1.0, v153
	v_mul_f32_e32 v148, v148, v155
	v_sqrt_f32_e32 v155, v148
	v_lshlrev_b32_e32 v148, 16, v205
	v_and_b32_e32 v149, 0xffff0000, v205
	v_pk_mul_f32 v[148:149], v[150:151], v[148:149]
	v_and_b32_e32 v147, 0xffff0000, v206
	v_pk_mul_f32 v[148:149], v[148:149], v[154:155]
	v_pk_mul_f32 v[146:147], v[138:139], v[146:147]
	v_pk_fma_f32 v[136:137], v[136:137], v[152:153], v[148:149]
	v_cvt_pk_bf16_f32 v144, v146, v147
	v_lshlrev_b32_e32 v146, 16, v207
	v_and_b32_e32 v147, 0xffff0000, v207
	v_pk_mul_f32 v[146:147], v[136:137], v[146:147]
	s_nop 0
	v_cvt_pk_bf16_f32 v145, v146, v147
	v_add_co_u32_e32 v146, vcc, s1, v142
	s_mov_b32 s1, 0x23a0b000
	s_nop 0
	v_addc_co_u32_e32 v147, vcc, 0, v143, vcc
	global_store_dwordx2 v[146:147], v[144:145], off offset:-4096
	v_add_co_u32_e32 v144, vcc, s1, v140
	s_mov_b32 s1, 0x1fa06000
	s_nop 0
	v_addc_co_u32_e32 v145, vcc, 0, v141, vcc
	s_nop 0
	v_add_co_u32_e32 v150, vcc, s1, v142
	s_mov_b32 s1, 0x1ba0b000
	s_nop 0
	v_addc_co_u32_e32 v151, vcc, 0, v143, vcc
	s_waitcnt vmcnt(8)
	v_lshlrev_b32_e32 v154, 16, v208
	v_and_b32_e32 v155, 0xffff0000, v208
	v_lshlrev_b32_e32 v158, 16, v209
	v_and_b32_e32 v159, 0xffff0000, v209
	v_lshlrev_b32_e32 v148, 16, v210
	v_and_b32_e32 v149, 0xffff0000, v210
	v_add_f32_e32 v144, v68, v154
	v_mul_f32_e32 v144, 0xbfb8aa3b, v144
	v_exp_f32_e32 v144, v144
	v_lshlrev_b32_e32 v160, 16, v211
	v_and_b32_e32 v161, 0xffff0000, v211
	v_and_b32_e32 v157, 0xffff0000, v212
	v_add_f32_e32 v144, 1.0, v144
	v_rcp_f32_e32 v145, v144
	v_add_f32_e32 v144, v64, v148
	v_mul_f32_e32 v144, 0xbfb8aa3b, v144
	v_exp_f32_e32 v144, v144
	v_mul_f32_e32 v145, v72, v145
	v_exp_f32_e32 v148, v145
	v_add_f32_e32 v144, 1.0, v144
	v_rcp_f32_e32 v144, v144
	v_sub_f32_e32 v145, 1.0, v148
	v_add_f32_e32 v154, 1.0, v148
	v_mul_f32_e32 v145, v145, v154
	v_sqrt_f32_e32 v154, v145
	v_add_f32_e32 v145, v69, v155
	v_mul_f32_e32 v145, 0xbfb8aa3b, v145
	v_exp_f32_e32 v145, v145
	s_nop 0
	v_add_f32_e32 v145, 1.0, v145
	v_rcp_f32_e32 v155, v145
	v_add_f32_e32 v145, v65, v149
	v_mul_f32_e32 v145, 0xbfb8aa3b, v145
	v_exp_f32_e32 v145, v145
	v_mul_f32_e32 v149, v73, v155
	v_exp_f32_e32 v149, v149
	v_add_f32_e32 v145, 1.0, v145
	v_rcp_f32_e32 v145, v145
	v_sub_f32_e32 v155, 1.0, v149
	v_add_f32_e32 v156, 1.0, v149
	v_mul_f32_e32 v155, v155, v156
	v_sqrt_f32_e32 v155, v155
	v_lshlrev_b32_e32 v156, 16, v212
	v_pk_mul_f32 v[144:145], v[144:145], v[156:157]
	v_add_f32_e32 v152, v70, v158
	v_pk_mul_f32 v[144:145], v[144:145], v[154:155]
	v_mul_f32_e32 v152, 0xbfb8aa3b, v152
	v_pk_fma_f32 v[138:139], v[138:139], v[148:149], v[144:145]
	v_add_co_u32_e32 v144, vcc, s1, v140
	v_exp_f32_e32 v152, v152
	s_nop 0
	v_addc_co_u32_e32 v145, vcc, 0, v141, vcc
	v_add_f32_e32 v152, 1.0, v152
	v_rcp_f32_e32 v152, v152
	v_add_f32_e32 v154, v66, v160
	v_mul_f32_e32 v154, 0xbfb8aa3b, v154
	v_exp_f32_e32 v154, v154
	v_mul_f32_e32 v152, v74, v152
	v_exp_f32_e32 v156, v152
	s_mov_b32 s1, 0x23a0d000
	v_add_f32_e32 v154, 1.0, v154
	v_rcp_f32_e32 v154, v154
	v_sub_f32_e32 v152, 1.0, v156
	v_add_f32_e32 v155, 1.0, v156
	v_mul_f32_e32 v152, v152, v155
	v_sqrt_f32_e32 v158, v152
	v_add_f32_e32 v152, v71, v159
	v_mul_f32_e32 v152, 0xbfb8aa3b, v152
	v_exp_f32_e32 v152, v152
	v_add_f32_e32 v155, v67, v161
	v_mul_f32_e32 v155, 0xbfb8aa3b, v155
	v_exp_f32_e32 v155, v155
	v_add_f32_e32 v152, 1.0, v152
	v_rcp_f32_e32 v152, v152
	v_add_f32_e32 v155, 1.0, v155
	v_rcp_f32_e32 v155, v155
	v_mul_f32_e32 v152, v75, v152
	v_exp_f32_e32 v157, v152
	v_lshlrev_b32_e32 v148, 16, v214
	v_sub_f32_e32 v152, 1.0, v157
	v_add_f32_e32 v159, 1.0, v157
	v_mul_f32_e32 v152, v152, v159
	v_sqrt_f32_e32 v159, v152
	v_lshlrev_b32_e32 v152, 16, v213
	v_and_b32_e32 v153, 0xffff0000, v213
	v_pk_mul_f32 v[152:153], v[154:155], v[152:153]
	v_and_b32_e32 v149, 0xffff0000, v214
	v_pk_mul_f32 v[152:153], v[152:153], v[158:159]
	v_pk_mul_f32 v[148:149], v[138:139], v[148:149]
	v_pk_fma_f32 v[136:137], v[136:137], v[156:157], v[152:153]
	v_cvt_pk_bf16_f32 v144, v148, v149
	v_lshlrev_b32_e32 v148, 16, v215
	v_and_b32_e32 v149, 0xffff0000, v215
	v_pk_mul_f32 v[148:149], v[136:137], v[148:149]
	s_nop 0
	v_cvt_pk_bf16_f32 v145, v148, v149
	global_store_dwordx2 v[146:147], v[144:145], off
	v_add_co_u32_e32 v144, vcc, s1, v140
	s_mov_b32 s1, 0x1ba0d000
	s_nop 0
	v_addc_co_u32_e32 v145, vcc, 0, v141, vcc
	s_nop 0
	s_nop 0
	s_waitcnt vmcnt(4)
	v_lshlrev_b32_e32 v150, 16, v216
	v_and_b32_e32 v151, 0xffff0000, v216
	v_lshlrev_b32_e32 v154, 16, v217
	v_and_b32_e32 v155, 0xffff0000, v217
	v_lshlrev_b32_e32 v146, 16, v218
	v_and_b32_e32 v147, 0xffff0000, v218
	v_add_f32_e32 v144, v68, v150
	v_mul_f32_e32 v144, 0xbfb8aa3b, v144
	v_exp_f32_e32 v144, v144
	v_lshlrev_b32_e32 v156, 16, v219
	v_and_b32_e32 v157, 0xffff0000, v219
	v_and_b32_e32 v153, 0xffff0000, v222
	v_add_f32_e32 v144, 1.0, v144
	v_rcp_f32_e32 v145, v144
	v_add_f32_e32 v144, v64, v146
	v_mul_f32_e32 v144, 0xbfb8aa3b, v144
	v_exp_f32_e32 v144, v144
	v_mul_f32_e32 v145, v72, v145
	v_exp_f32_e32 v146, v145
	v_add_f32_e32 v144, 1.0, v144
	v_rcp_f32_e32 v144, v144
	v_sub_f32_e32 v145, 1.0, v146
	v_add_f32_e32 v150, 1.0, v146
	v_mul_f32_e32 v145, v145, v150
	v_sqrt_f32_e32 v150, v145
	v_add_f32_e32 v145, v69, v151
	v_mul_f32_e32 v145, 0xbfb8aa3b, v145
	v_exp_f32_e32 v145, v145
	s_nop 0
	v_add_f32_e32 v145, 1.0, v145
	v_rcp_f32_e32 v151, v145
	v_add_f32_e32 v145, v65, v147
	v_mul_f32_e32 v145, 0xbfb8aa3b, v145
	v_exp_f32_e32 v145, v145
	v_mul_f32_e32 v147, v73, v151
	v_exp_f32_e32 v147, v147
	v_add_f32_e32 v145, 1.0, v145
	v_rcp_f32_e32 v145, v145
	v_sub_f32_e32 v151, 1.0, v147
	v_add_f32_e32 v152, 1.0, v147
	v_mul_f32_e32 v151, v151, v152
	v_sqrt_f32_e32 v151, v151
	v_lshlrev_b32_e32 v152, 16, v222
	v_pk_mul_f32 v[144:145], v[144:145], v[152:153]
	v_add_f32_e32 v148, v70, v154
	v_pk_mul_f32 v[144:145], v[144:145], v[150:151]
	v_mul_f32_e32 v148, 0xbfb8aa3b, v148
	v_pk_fma_f32 v[138:139], v[138:139], v[146:147], v[144:145]
	v_add_co_u32_e32 v144, vcc, s1, v140
	v_exp_f32_e32 v148, v148
	s_nop 0
	v_addc_co_u32_e32 v145, vcc, 0, v141, vcc
	v_add_f32_e32 v148, 1.0, v148
	v_rcp_f32_e32 v148, v148
	v_add_f32_e32 v150, v66, v156
	v_mul_f32_e32 v150, 0xbfb8aa3b, v150
	v_exp_f32_e32 v150, v150
	v_mul_f32_e32 v148, v74, v148
	v_exp_f32_e32 v152, v148
	s_mov_b32 s1, 0x21a06000
	v_add_f32_e32 v150, 1.0, v150
	v_rcp_f32_e32 v150, v150
	v_sub_f32_e32 v148, 1.0, v152
	v_add_f32_e32 v151, 1.0, v152
	v_mul_f32_e32 v148, v148, v151
	v_sqrt_f32_e32 v154, v148
	v_add_f32_e32 v148, v71, v155
	v_mul_f32_e32 v148, 0xbfb8aa3b, v148
	v_exp_f32_e32 v148, v148
	v_add_f32_e32 v151, v67, v157
	v_mul_f32_e32 v151, 0xbfb8aa3b, v151
	v_exp_f32_e32 v151, v151
	v_add_f32_e32 v148, 1.0, v148
	v_rcp_f32_e32 v148, v148
	v_add_f32_e32 v151, 1.0, v151
	v_rcp_f32_e32 v151, v151
	v_mul_f32_e32 v148, v75, v148
	v_exp_f32_e32 v153, v148
	v_lshlrev_b32_e32 v146, 16, v224
	v_sub_f32_e32 v148, 1.0, v153
	v_add_f32_e32 v155, 1.0, v153
	v_mul_f32_e32 v148, v148, v155
	v_sqrt_f32_e32 v155, v148
	v_lshlrev_b32_e32 v148, 16, v223
	v_and_b32_e32 v149, 0xffff0000, v223
	v_pk_mul_f32 v[148:149], v[150:151], v[148:149]
	v_and_b32_e32 v147, 0xffff0000, v224
	v_pk_mul_f32 v[148:149], v[148:149], v[154:155]
	v_pk_mul_f32 v[146:147], v[138:139], v[146:147]
	v_pk_fma_f32 v[136:137], v[136:137], v[152:153], v[148:149]
	v_cvt_pk_bf16_f32 v144, v146, v147
	v_lshlrev_b32_e32 v146, 16, v225
	v_and_b32_e32 v147, 0xffff0000, v225
	v_pk_mul_f32 v[146:147], v[136:137], v[146:147]
	s_nop 0
	v_cvt_pk_bf16_f32 v145, v146, v147
	v_add_co_u32_e32 v146, vcc, s1, v142
	s_mov_b32 s1, 0x23a0f000
	s_nop 0
	v_addc_co_u32_e32 v147, vcc, 0, v143, vcc
	global_store_dwordx2 v[146:147], v[144:145], off
	v_add_co_u32_e32 v144, vcc, s1, v140
	s_mov_b32 s1, 0x1fa07000
	s_nop 0
	v_addc_co_u32_e32 v145, vcc, 0, v141, vcc
	s_nop 0
	v_add_co_u32_e32 v148, vcc, s1, v142
	s_mov_b32 s1, 0x1ba0f000
	s_nop 0
	v_addc_co_u32_e32 v149, vcc, 0, v143, vcc
	v_add_co_u32_e32 v140, vcc, s1, v140
	s_waitcnt vmcnt(0)
	v_lshlrev_b32_e32 v150, 16, v226
	v_addc_co_u32_e32 v141, vcc, 0, v141, vcc
	v_and_b32_e32 v151, 0xffff0000, v226
	v_lshlrev_b32_e32 v154, 16, v227
	v_and_b32_e32 v155, 0xffff0000, v227
	v_lshlrev_b32_e32 v146, 16, v232
	v_and_b32_e32 v147, 0xffff0000, v232
	v_add_f32_e32 v144, v68, v150
	v_mul_f32_e32 v144, 0xbfb8aa3b, v144
	v_exp_f32_e32 v144, v144
	v_lshlrev_b32_e32 v156, 16, v233
	v_and_b32_e32 v157, 0xffff0000, v233
	v_and_b32_e32 v153, 0xffff0000, v234
	v_add_f32_e32 v144, 1.0, v144
	v_rcp_f32_e32 v145, v144
	v_add_f32_e32 v144, v64, v146
	v_mul_f32_e32 v144, 0xbfb8aa3b, v144
	v_exp_f32_e32 v144, v144
	v_mul_f32_e32 v145, v72, v145
	v_exp_f32_e32 v146, v145
	v_add_co_u32_e32 v142, vcc, 0x21a07000, v142
	v_add_f32_e32 v144, 1.0, v144
	v_sub_f32_e32 v145, 1.0, v146
	v_add_f32_e32 v150, 1.0, v146
	v_mul_f32_e32 v145, v145, v150
	v_sqrt_f32_e32 v150, v145
	v_add_f32_e32 v145, v69, v151
	v_mul_f32_e32 v145, 0xbfb8aa3b, v145
	v_exp_f32_e32 v145, v145
	v_rcp_f32_e32 v144, v144
	v_addc_co_u32_e32 v143, vcc, 0, v143, vcc
	v_add_f32_e32 v145, 1.0, v145
	v_rcp_f32_e32 v151, v145
	v_add_f32_e32 v145, v65, v147
	v_mul_f32_e32 v145, 0xbfb8aa3b, v145
	v_exp_f32_e32 v145, v145
	v_mul_f32_e32 v147, v73, v151
	v_exp_f32_e32 v147, v147
	v_add_f32_e32 v145, 1.0, v145
	v_rcp_f32_e32 v145, v145
	v_sub_f32_e32 v151, 1.0, v147
	v_add_f32_e32 v152, 1.0, v147
	v_mul_f32_e32 v151, v151, v152
	v_lshlrev_b32_e32 v152, 16, v234
	v_add_f32_e32 v148, v70, v154
	v_mul_f32_e32 v148, 0xbfb8aa3b, v148
	v_exp_f32_e32 v148, v148
	v_sqrt_f32_e32 v151, v151
	v_pk_mul_f32 v[144:145], v[144:145], v[152:153]
	v_add_f32_e32 v148, 1.0, v148
	v_rcp_f32_e32 v148, v148
	v_pk_mul_f32 v[144:145], v[144:145], v[150:151]
	v_add_f32_e32 v150, v66, v156
	v_mul_f32_e32 v150, 0xbfb8aa3b, v150
	v_mul_f32_e32 v148, v74, v148
	v_exp_f32_e32 v152, v148
	v_exp_f32_e32 v150, v150
	v_pk_fma_f32 v[138:139], v[138:139], v[146:147], v[144:145]
	v_sub_f32_e32 v148, 1.0, v152
	v_add_f32_e32 v151, 1.0, v152
	v_mul_f32_e32 v148, v148, v151
	v_sqrt_f32_e32 v154, v148
	v_add_f32_e32 v148, v71, v155
	v_mul_f32_e32 v148, 0xbfb8aa3b, v148
	v_exp_f32_e32 v148, v148
	v_add_f32_e32 v151, v67, v157
	v_mul_f32_e32 v151, 0xbfb8aa3b, v151
	v_exp_f32_e32 v151, v151
	v_add_f32_e32 v148, 1.0, v148
	v_rcp_f32_e32 v148, v148
	v_add_f32_e32 v150, 1.0, v150
	v_add_f32_e32 v151, 1.0, v151
	v_rcp_f32_e32 v150, v150
	v_mul_f32_e32 v148, v75, v148
	v_exp_f32_e32 v153, v148
	v_rcp_f32_e32 v151, v151
	v_lshlrev_b32_e32 v144, 16, v238
	v_and_b32_e32 v145, 0xffff0000, v238
	v_sub_f32_e32 v148, 1.0, v153
	v_add_f32_e32 v155, 1.0, v153
	v_mul_f32_e32 v148, v148, v155
	v_sqrt_f32_e32 v155, v148
	v_lshlrev_b32_e32 v148, 16, v235
	v_and_b32_e32 v149, 0xffff0000, v235
	v_pk_mul_f32 v[148:149], v[150:151], v[148:149]
	v_pk_mul_f32 v[144:145], v[138:139], v[144:145]
	v_pk_mul_f32 v[148:149], v[148:149], v[154:155]
	v_cvt_pk_bf16_f32 v140, v144, v145
	v_pk_fma_f32 v[136:137], v[136:137], v[152:153], v[148:149]
	v_lshlrev_b32_e32 v144, 16, v239
	v_and_b32_e32 v145, 0xffff0000, v239
	v_pk_mul_f32 v[144:145], v[136:137], v[144:145]
	s_nop 0
	v_cvt_pk_bf16_f32 v141, v144, v145
	global_store_dwordx2 v[142:143], v[140:141], off
	s_cbranch_scc0 .LBB0_1021
	v_add_u32_e32 v192, s96, v192
	s_mov_b32 s0, 0x1ffff
	v_cmp_lt_i32_e32 vcc, s0, v192
	v_mov_b64_e32 v[134:135], v[130:131]
	v_mov_b64_e32 v[138:139], v[122:123]
	v_mov_b64_e32 v[142:143], v[114:115]
	v_mov_b64_e32 v[150:151], v[106:107]
	v_mov_b64_e32 v[158:159], v[98:99]
	v_mov_b64_e32 v[166:167], v[90:91]
	v_mov_b64_e32 v[146:147], v[126:127]
	v_mov_b64_e32 v[154:155], v[118:119]
	v_mov_b64_e32 v[162:163], v[110:111]
	v_mov_b64_e32 v[170:171], v[102:103]
	v_mov_b64_e32 v[174:175], v[94:95]
	v_mov_b64_e32 v[178:179], v[86:87]
	v_add_u32_e32 v193, s2, v193
	s_or_b64 s[92:93], vcc, s[92:93]
	v_mov_b64_e32 v[132:133], v[128:129]
	v_mov_b64_e32 v[136:137], v[120:121]
	v_mov_b64_e32 v[140:141], v[112:113]
	v_mov_b64_e32 v[148:149], v[104:105]
	v_mov_b64_e32 v[156:157], v[96:97]
	v_mov_b64_e32 v[164:165], v[88:89]
	v_mov_b64_e32 v[144:145], v[124:125]
	v_mov_b64_e32 v[152:153], v[116:117]
	v_mov_b64_e32 v[160:161], v[108:109]
	v_mov_b64_e32 v[168:169], v[100:101]
	v_mov_b64_e32 v[172:173], v[92:93]
	v_mov_b64_e32 v[176:177], v[84:85]
	s_andn2_b64 exec, exec, s[92:93]
	s_cbranch_execnz .LBB0_976
